# combo2 + static prio for waves 4-7 in NA units as well
# baseline (speedup 1.0000x reference)
; __device__ __forceinline__ int opaque_tid() { int t; asm volatile("v_mov_b32 %0, %1" : "=v"(t) : "v"((int)threadIdx.x)); return t; }
; __global__ void __launch_bounds__(NTHREADS, 2) mega_fwd(Params P) {
;     ...
;             for (;;) {
;                 if (opaque_tid() == 0) qslot[0] = (int)atomicAdd(ctl + 64 * (l + 1), 1u);
;                 __syncthreads();
;                 const int idx = __builtin_amdgcn_readfirstlane(qslot[0]);
;                 __syncthreads();
.LBB0_441:
	s_setprio 0
	v_mov_b32 v0, v214
	s_nop 0
	v_cmp_eq_u32_e32 vcc, 0, v0
	s_and_saveexec_b64 s[0:1], vcc
	s_cbranch_execz .LBB0_443
	s_mov_b64 s[2:3], s[76:77]
	s_lshl_b64 s[4:5], s[60:61], 2
	s_add_u32 s2, s2, s4
	s_addc_u32 s3, s3, s5
	v_mov_b64_e32 v[2:3], s[2:3]
	s_waitcnt vmcnt(0)
	flat_atomic_add v0, v[2:3], v218 offset:256 sc0
	v_readlane_b32 s2, v254, 42
	s_nop 1
	v_mov_b32_e32 v2, s2
	s_waitcnt vmcnt(0) lgkmcnt(0)
	ds_write_b32 v2, v0

; #define DMA_K(t, slot) glds16s(kvo, Kh + (long)TROW(t) * PITCH, (unsigned)__builtin_amdgcn_readfirstlane(kdst + (slot)))
; #define DMA_V(t, slot) glds16s(vvo, Vh + (long)TROW(t) * PITCH, (unsigned)__builtin_amdgcn_readfirstlane(vdst + (slot)))
;     ...
;     const unsigned kvo = (unsigned)((lane * PITCH + wid * 8) * 2);
;     const unsigned vvo = (unsigned)(((16 * (wid & 3) + (lane >> 2)) * PITCH + (wid >> 2) * 32 + (lane & 3) * 8) * 2);
;     const unsigned kdst = lds0 + LDS_K + wid * 1024, vdst = lds0 + LDS_V + wid * 1024;
;     ...
;     const char* Kbase = shm + LDS_K; bf16x8 kf[8];
;     const lds_cptr shm3 = (lds_cptr)shm; const lds_cptr kp0 = shm3 + LDS_K + hi * 1024 + r32 * 16; const lds_cptr vp0 = shm3 + LDS_V + ((lane >> 4) & 1) * 32 + (lane & 3) * 8 + (4 * hi + ((lane & 15) >> 2)) * 64;
;     DMA_K(0, 0); DMA_V(0, 0); DMA_K(1, SLOTB);
;     bf16x8 qr[4];
; #pragma unroll
;     for (int d0 = 0; d0 < 4; ++d0) qr[d0] = *reinterpret_cast<const bf16x8*>(&Qw[(long)r32 * PITCH + d0 * 16 + hi * 8]);
;     float mhat = (MODE == 0) ? bref : 0.f, l_reg = 0.f; f32x16 o[2]; o[0] = f32x16{}; o[1] = f32x16{}; f32x16 negm = f32x16{};
; __global__ void __launch_bounds__(NTHREADS, 2) mega_fwd(Params P) {
;     ...
;                     __syncthreads();
;                     const int r0 = 4 * rblk, klo = min(max(r0 - 4, 0), 120), khi = min(max(r0 - 1, 0), 120) + 7; const int nlt = (khi - klo + 2) & ~1;
;                     ap::unit<8, 1>(qkv + (rb + 256 * rblk) * DIN + C_QA + 64 * h, qkv + rb * DIN + C_KA + 64 * h, qkv + rb * DIN + C_VA + 64 * h,
;                                    omix + (rb + 256 * rblk) * DM + 64 * h, ssb + (rb + 256 * rblk) * 4 + 0, 4 + nlt, (char*)lds, klo, r0);
.LBB0_589:
	s_or_b64 exec, exec, s[0:1]
	s_and_b32 s3, 0xffff, s3
	s_lshl_b32 s0, s3, 2
	v_sub_u32_e64 v2, s0, 1 clamp
	v_sub_u32_e64 v0, s0, 4 clamp
	v_readfirstlane_b32 s1, v2
	s_min_u32 s1, s1, 0x78
	v_readfirstlane_b32 s89, v0
	s_sub_i32 s1, s1, s89
	s_add_i32 s19, s1, 7
	s_and_b32 s21, s19, -2
	s_lshl_b32 s1, s3, 8
	s_cmp_gt_u32 s2, 5
	v_writelane_b32 v252, s3, 27
	s_cselect_b64 s[2:3], -1, 0
	v_writelane_b32 v252, s2, 28
	s_waitcnt vmcnt(0) lgkmcnt(0)
	s_barrier
	v_readfirstlane_b32 s100, v214
	s_nop 0
	s_lshr_b32 s100, s100, 6
	s_cmp_ge_u32 s100, 4
	s_cbranch_scc0 .Lna_prio_skip
	s_setprio 1
.Lna_prio_skip:
	v_writelane_b32 v252, s3, 29
	s_and_b64 s[2:3], s[2:3], exec
	s_cselect_b32 s4, 0x2100, 0
	s_cselect_b32 s5, 0x2520000, 0
	s_add_i32 s86, s4, s1
	s_mov_b64 s[2:3], s[76:77]
	s_mul_hi_u32 s4, s86, 0x1200
	v_writelane_b32 v252, s86, 30
	s_mul_i32 s6, s86, 0x1200
	s_add_u32 s6, s2, s6
	s_addc_u32 s4, s3, s4
	s_lshl_b32 s8, s28, 7
	s_mov_b64 s[2:3], s[76:77]
	s_add_u32 s10, s6, s8
	s_addc_u32 s4, s4, 0
	s_add_u32 s2, s2, s5
	s_addc_u32 s3, s3, 0
	s_add_u32 s6, s2, s8
	s_addc_u32 s7, s3, 0
	s_add_u32 s93, s6, 0xe400b00
	s_mov_b64 s[2:3], s[76:77]
	s_addc_u32 s94, s7, 0
	s_add_u32 s2, s2, s5
	s_addc_u32 s3, s3, 0
	s_add_u32 s8, s2, s8
	s_addc_u32 s9, s3, 0
	s_mov_b64 s[2:3], s[76:77]
	v_writelane_b32 v252, s87, 31
	s_add_u32 s91, s8, 0xe400e00
	v_writelane_b32 v252, s2, 32
	s_addc_u32 s92, s9, 0
	s_mov_b32 s95, 1
	v_writelane_b32 v252, s3, 33
	s_mov_b64 s[2:3], s[76:77]
	v_mov_b32 v223, v214
	s_mov_b32 s72, 0
	v_readfirstlane_b32 s5, v223
	v_writelane_b32 v252, s2, 34
	s_ashr_i32 s12, s5, 6
	s_lshl_b32 s16, s12, 5
	v_writelane_b32 v252, s3, 35
	s_mul_i32 s2, s12, 0x24000
	s_mul_hi_i32 s3, s16, 0x1200
	s_add_u32 s10, s10, s2
	s_addc_u32 s11, s4, s3
	s_lshl_b32 s2, s12, 4
	v_and_b32_e32 v224, 63, v223
	v_mov_b32_e32 v0, s2
	v_mad_u32_u24 v234, v224, s80, v0
	v_bfe_u32 v0, v223, 2, 4
	v_and_or_b32 v0, s2, 48, v0
	s_ashr_i32 s2, s5, 3
	s_and_b32 s3, s5, 0x3fffffc0
	s_and_b32 s2, s2, 0x7fffffe0
	s_lshl_b32 s4, s12, 10
	v_mov_b32_e32 v2, s2
	s_cmp_lg_u32 0, -1
	v_mad_u32_u24 v0, v0, s81, v2
	v_lshlrev_b32_e32 v2, 3, v223
	s_cselect_b32 s2, 0, 0
	v_and_b32_e32 v227, 24, v2
	s_add_i32 s4, s4, s2
	v_and_b32_e32 v225, 31, v223
	v_or_b32_e32 v0, v0, v227
	s_add_i32 s90, s4, 0x6000
	v_lshlrev_b32_e32 v235, 1, v0
	v_writelane_b32 v252, s12, 36
	s_add_u32 s12, s6, 0x10800b00
	v_mul_u32_u24_e32 v0, 0x900, v225
	v_bfe_u32 v230, v223, 5, 1
	s_addc_u32 s13, s7, 0
	v_lshlrev_b32_e32 v0, 1, v0
	s_mov_b32 s2, m0
	s_mov_b32 m0, s4
	s_nop 0
	global_load_lds_dwordx4 v234, s[12:13]
	s_mov_b32 m0, s2
	s_add_u32 s12, s8, 0x10800e00
	v_lshl_or_b32 v0, v230, 4, v0
	s_addc_u32 s13, s9, 0
	v_lshl_add_u64 v[2:3], s[10:11], 0, v[0:1]
	s_mov_b32 s2, m0
	s_mov_b32 m0, s90
	s_nop 0
	global_load_lds_dwordx4 v235, s[12:13]
	s_mov_b32 m0, s2
	s_add_u32 s12, s6, 0x10848b00
	v_add_co_u32_e32 v4, vcc, s82, v2
	s_addc_u32 s13, s7, 0
	s_add_i32 s2, s4, 0x2000
	s_mov_b32 s14, m0
	s_mov_b32 m0, s2
	s_nop 0
	global_load_lds_dwordx4 v234, s[12:13]
	s_mov_b32 m0, s14
	v_addc_co_u32_e32 v5, vcc, 0, v3, vcc
	flat_load_dwordx4 v[144:147], v[4:5] offset:2048
	s_mov_b64 s[10:11], 0xe400800
	v_lshl_add_u64 v[2:3], v[2:3], 0, s[10:11]
	flat_load_dwordx4 v[140:143], v[2:3] offset:32
	flat_load_dwordx4 v[136:139], v[2:3] offset:64
	flat_load_dwordx4 v[132:135], v[2:3] offset:96
	s_ashr_i32 vcc_lo, s5, 7
	s_add_i32 s2, vcc_lo, s0
	s_max_i32 s10, s2, 4
	s_add_i32 s10, s10, -4
	s_add_u32 s12, s6, 0x10890b00
	v_lshlrev_b32_e32 v0, 10, v230
	v_lshlrev_b32_e32 v2, 4, v225
	v_writelane_b32 v252, s2, 37
	s_addc_u32 s13, s7, 0
	s_add_i32 s2, s4, 0x4000
	s_mov_b32 s11, m0
	s_mov_b32 m0, s2
	s_nop 0
	global_load_lds_dwordx4 v234, s[12:13]
	s_mov_b32 m0, s11
	v_add3_u32 v236, 0, v0, v2
	s_waitcnt vmcnt(3) lgkmcnt(0)
	s_barrier
	ds_read_b128 v[2:5], v236
	ds_read_b128 v[6:9], v236 offset:512
	s_lshl_b32 s3, s3, 2
	s_add_i32 s3, s3, 0
	s_min_u32 s20, s10, 0x78
	s_add_u32 s6, s6, 0x108d8b00
	s_waitcnt vmcnt(0) lgkmcnt(0)
	v_mfma_f32_32x32x16_bf16 v[34:49], v[2:5], v[144:147], 0
	s_addc_u32 s7, s7, 0
	s_mov_b32 s12, s16
	v_writelane_b32 v252, s12, 38
	v_lshlrev_b32_e32 v0, 1, v223
	v_and_b32_e32 v228, 32, v0
	v_writelane_b32 v252, s13, 39
	v_writelane_b32 v252, s19, 40
	v_mfma_f32_32x32x16_bf16 v[18:33], v[6:9], v[144:147], 0
	ds_read_b128 v[2:5], v236 offset:2048
	ds_read_b128 v[6:9], v236 offset:2560
	v_lshlrev_b32_e32 v226, 8, v230
	v_and_or_b32 v233, s16, 32, v225
	v_add_u32_e32 v0, 0, v228
	v_lshlrev_b32_e32 v196, 2, v225
	s_movk_i32 s88, 0x2000
	s_movk_i32 s2, 0x4000
	s_waitcnt lgkmcnt(1)
	v_mfma_f32_32x32x16_bf16 v[34:49], v[2:5], v[140:143], v[34:49]
	ds_read_b128 v[2:5], v236 offset:4608
	ds_read_b128 v[10:13], v236 offset:4096
	v_add_u32_e32 v238, s3, v196
	s_waitcnt lgkmcnt(2)
	v_mfma_f32_32x32x16_bf16 v[18:33], v[6:9], v[140:143], v[18:33]
	s_waitcnt lgkmcnt(0)
	v_mfma_f32_32x32x16_bf16 v[34:49], v[10:13], v[136:139], v[34:49]
	ds_read_b128 v[6:9], v236 offset:6656
	ds_read_b128 v[10:13], v236 offset:6144
	v_mfma_f32_32x32x16_bf16 v[18:33], v[2:5], v[136:139], v[18:33]
	v_lshlrev_b32_e32 v2, 4, v223
	v_and_or_b32 v229, v2, s83, v226
	v_sub_u32_e64 v2, v233, 8 clamp
	v_add3_u32 v237, v0, v227, v229
	v_min_u32_e32 v232, 48, v2
	s_waitcnt lgkmcnt(0)
	v_mfma_f32_32x32x16_bf16 v[34:49], v[10:13], v[132:135], v[34:49]
	v_mfma_f32_32x32x16_bf16 v[18:33], v[6:9], v[132:135], v[18:33]
	s_nop 15
	s_nop 7
	s_waitcnt vmcnt(0) lgkmcnt(0)
	s_barrier
; #define WAIT_BAR(N) asm volatile("s_waitcnt vmcnt(" #N ") lgkmcnt(0)\n\ts_barrier" ::: "memory")
; #define DMA_K(t, slot) glds16s(kvo, Kh + (long)TROW(t) * PITCH, (unsigned)__builtin_amdgcn_readfirstlane(kdst + (slot)))
; #define DMA_V(t, slot) glds16s(vvo, Vh + (long)TROW(t) * PITCH, (unsigned)__builtin_amdgcn_readfirstlane(vdst + (slot)))
; #define ROT() do { sl_prev = sl_cur; sl_cur = sl_next; sl_next = (sl_next == (NSLOT - 1) * SLOTB) ? 0 : sl_next + SLOTB; } while (0)
;     ...
;     DMA_K(2, 2 * SLOTB);
;     WAIT_BAR(3);
;     qkt(pA0, pA1, Kbase, qr, negm, r32, hi); asm volatile("s_nop 15\n\ts_nop 7" : "+v"(pA0), "+v"(pA1));
;     START(pA0, pA1);
;     _Pragma("unroll") for (int r = 0; r < 16; ++r) pA1[r] = __builtin_amdgcn_exp2f(pA1[r]);
;     WAIT_BAR(0);
;     DMA_K(3, 0); DMA_V(1, SLOTB);
;     ROT();
;     kload8(kf, kp0 + sl_cur);
	s_mov_b32 s10, m0
	s_mov_b32 m0, s4
	s_nop 0
	global_load_lds_dwordx4 v234, s[6:7]
	s_mov_b32 m0, s10
	s_add_u32 s6, s8, 0x10848e00
	v_max3_f32 v3, v34, v35, v18
	v_max3_f32 v4, v36, v37, v19
	s_addc_u32 s7, s9, 0
	v_max3_f32 v3, v3, v20, v21
	v_max3_f32 v4, v4, v40, v41
	s_add_i32 s8, s4, 0x8000
	v_max3_f32 v3, v3, v38, v39
	v_max3_f32 v4, v4, v24, v25
	s_mov_b32 s9, m0
	s_mov_b32 m0, s8
	s_nop 0
	global_load_lds_dwordx4 v235, s[6:7]
	s_mov_b32 m0, s9
	ds_read_b128 v[176:179], v236 offset:8192
	ds_read_b128 v[168:171], v236 offset:8704
	ds_read_b128 v[172:175], v236 offset:10240
	ds_read_b128 v[164:167], v236 offset:10752
	ds_read_b128 v[160:163], v236 offset:12288
	ds_read_b128 v[156:159], v236 offset:12800
	ds_read_b128 v[152:155], v236 offset:14336
	ds_read_b128 v[148:151], v236 offset:14848
	v_max3_f32 v3, v3, v22, v23
	v_max3_f32 v4, v4, v44, v45
	v_cmp_gt_u32_e64 s[6:7], 32, v224
	v_max3_f32 v3, v3, v42, v43
	v_max3_f32 v4, v4, v28, v29
	s_waitcnt vmcnt(2) lgkmcnt(0)
	s_barrier
	s_cmp_lt_i32 s19, 2
	v_max3_f32 v3, v3, v26, v27
	v_max3_f32 v4, v4, v48, v49
	s_nop 0
	v_writelane_b32 v252, s6, 41
	v_max3_f32 v3, v3, v46, v47
	v_max3_f32 v4, v4, v32, v33
	s_nop 0
	v_max3_f32 v3, v3, v30, v31
	s_nop 0
	v_max_f32_e32 v3, v3, v4
	v_writelane_b32 v252, s7, 42
	v_mov_b32_e32 v4, v3
	s_nop 1
	v_permlane32_swap_b32_e32 v3, v4
	v_max_f32_e32 v3, v3, v4
	v_writelane_b32 v252, s48, 43
	v_add_f32_e32 v231, v1, v3
	v_sub_f32_e32 v4, v34, v3
	v_sub_f32_e32 v5, v18, v3
	v_sub_f32_e32 v6, v35, v3
	v_sub_f32_e32 v7, v19, v3
	v_sub_f32_e32 v8, v36, v3
	v_sub_f32_e32 v9, v20, v3
	v_sub_f32_e32 v10, v37, v3
	v_sub_f32_e32 v11, v21, v3
	v_sub_f32_e32 v12, v38, v3
	v_sub_f32_e32 v13, v22, v3
	v_sub_f32_e32 v14, v39, v3
	v_sub_f32_e32 v15, v23, v3
	v_sub_f32_e32 v17, v40, v3
	v_sub_f32_e32 v18, v24, v3
	v_sub_f32_e32 v19, v41, v3
	v_sub_f32_e32 v20, v25, v3
	v_sub_f32_e32 v21, v42, v3
	v_sub_f32_e32 v22, v26, v3
	v_sub_f32_e32 v23, v43, v3
	v_sub_f32_e32 v24, v27, v3
	v_sub_f32_e32 v25, v44, v3
	v_sub_f32_e32 v26, v28, v3
	v_sub_f32_e32 v27, v45, v3
	v_sub_f32_e32 v28, v29, v3
	v_sub_f32_e32 v29, v46, v3
	v_sub_f32_e32 v30, v30, v3
	v_sub_f32_e32 v34, v47, v3
	v_sub_f32_e32 v31, v31, v3
	v_sub_f32_e32 v35, v48, v3
	v_sub_f32_e32 v32, v32, v3
	v_sub_f32_e32 v36, v49, v3
	v_sub_f32_e32 v3, v33, v3
	s_nop 0
	v_exp_f32_e32 v64, v4
	v_exp_f32_e32 v65, v6
	v_exp_f32_e32 v66, v8
	v_exp_f32_e32 v67, v10
	v_exp_f32_e32 v68, v12
	v_exp_f32_e32 v69, v14
	v_exp_f32_e32 v70, v17
	v_exp_f32_e32 v71, v19
	v_exp_f32_e32 v72, v21
	v_exp_f32_e32 v73, v23
	v_exp_f32_e32 v74, v25
	v_exp_f32_e32 v75, v27
	v_exp_f32_e32 v76, v29
	v_exp_f32_e32 v77, v34
	v_exp_f32_e32 v78, v35
	v_exp_f32_e32 v79, v36
	v_exp_f32_e32 v80, v5
	v_exp_f32_e32 v81, v7
	v_exp_f32_e32 v82, v9
	v_exp_f32_e32 v83, v11
	v_exp_f32_e32 v84, v13
	v_exp_f32_e32 v85, v15
	v_exp_f32_e32 v86, v18
	v_exp_f32_e32 v87, v20
	v_exp_f32_e32 v88, v22
	v_exp_f32_e32 v89, v24
	v_exp_f32_e32 v90, v26
	v_exp_f32_e32 v91, v28
	v_exp_f32_e32 v92, v30
	v_exp_f32_e32 v93, v31
	v_exp_f32_e32 v94, v32
	v_exp_f32_e32 v95, v3
	v_writelane_b32 v252, vcc_lo, 44
	s_cbranch_scc1 .LBB0_689
;     ...
;     float mhat = (MODE == 0) ? bref : 0.f, l_reg = 0.f; f32x16 o[2]; o[0] = f32x16{}; o[1] = f32x16{}; f32x16 negm = f32x16{};
;     if (MODE == 0) { _Pragma("unroll") for (int r = 0; r < 16; ++r) negm[r] = -bref; }
;     if (MODE != 1) asm volatile("" : "+v"(negm));
;     int na_gr = 0, na_rs = 0, na_qc = 0, na_cs = 0;
;     if (MODE == 1) { na_gr = r0 + (wid >> 1); na_rs = min(max(na_gr - 4, 0), 120); na_qc = 32 * (wid & 1) + r32; na_cs = min(max(na_qc - 8, 0), 48); }
	v_lshlrev_b32_e32 v0, 2, v230
	v_sub_u32_e32 v2, v0, v232
	v_cmp_gt_u32_e64 s[6:7], 16, v2
	v_or_b32_e32 v2, 32, v0
	v_sub_u32_e32 v2, v2, v232
	v_cmp_gt_u32_e64 s[8:9], 16, v2
	v_or_b32_e32 v2, 1, v0
	v_sub_u32_e32 v2, v2, v232
	v_cmp_gt_u32_e64 s[10:11], 16, v2
	v_or_b32_e32 v2, 33, v0
	v_sub_u32_e32 v2, v2, v232
	v_cmp_gt_u32_e64 s[12:13], 16, v2
	v_or_b32_e32 v2, 2, v0
	v_sub_u32_e32 v2, v2, v232
	v_cmp_gt_u32_e64 s[14:15], 16, v2
	v_or_b32_e32 v2, 34, v0
	v_sub_u32_e32 v2, v2, v232
	v_cmp_gt_u32_e64 s[16:17], 16, v2
	v_or_b32_e32 v2, 3, v0
	v_sub_u32_e32 v2, v2, v232
	v_cmp_gt_u32_e64 s[18:19], 16, v2
	v_or_b32_e32 v2, 35, v0
	v_sub_u32_e32 v2, v2, v232
	s_mov_b32 s74, s20
	s_mov_b32 s2, s21
	v_cmp_gt_u32_e64 s[20:21], 16, v2
	v_or_b32_e32 v2, 8, v0
	v_sub_u32_e32 v2, v2, v232
	v_cmp_gt_u32_e64 s[22:23], 16, v2
	v_or_b32_e32 v2, 40, v0
	v_sub_u32_e32 v2, v2, v232
	v_cmp_gt_u32_e64 s[24:25], 16, v2
	v_or_b32_e32 v2, 9, v0
	v_sub_u32_e32 v2, v2, v232
	v_cmp_gt_u32_e64 s[26:27], 16, v2
	v_or_b32_e32 v2, 41, v0
	v_sub_u32_e32 v2, v2, v232
	v_writelane_b32 v252, s28, 45
	v_cmp_gt_u32_e64 s[28:29], 16, v2
	v_or_b32_e32 v2, 10, v0
	v_sub_u32_e32 v2, v2, v232
	v_cmp_gt_u32_e64 s[30:31], 16, v2
	v_or_b32_e32 v2, 42, v0
	v_sub_u32_e32 v2, v2, v232
	v_cmp_gt_u32_e64 s[34:35], 16, v2
	v_or_b32_e32 v2, 11, v0
	v_sub_u32_e32 v2, v2, v232
	v_cmp_gt_u32_e64 s[36:37], 16, v2
	v_or_b32_e32 v2, 43, v0
	v_sub_u32_e32 v2, v2, v232
	v_cmp_gt_u32_e64 s[38:39], 16, v2
	v_or_b32_e32 v2, 16, v0
	v_sub_u32_e32 v2, v2, v232
	v_cmp_gt_u32_e64 s[40:41], 16, v2
	v_or_b32_e32 v2, 48, v0
	v_sub_u32_e32 v2, v2, v232
	v_cmp_gt_u32_e64 s[42:43], 16, v2
	v_or_b32_e32 v2, 17, v0
	v_sub_u32_e32 v2, v2, v232
	v_cmp_gt_u32_e64 s[44:45], 16, v2
	v_or_b32_e32 v2, 49, v0
	v_sub_u32_e32 v2, v2, v232
	v_cmp_gt_u32_e64 s[46:47], 16, v2
	v_or_b32_e32 v2, 18, v0
	v_sub_u32_e32 v2, v2, v232
	v_cmp_gt_u32_e64 s[48:49], 16, v2
	v_or_b32_e32 v2, 50, v0
	v_sub_u32_e32 v2, v2, v232
	v_cmp_gt_u32_e64 s[50:51], 16, v2
	v_or_b32_e32 v2, 19, v0
	v_sub_u32_e32 v2, v2, v232
	v_cmp_gt_u32_e64 s[52:53], 16, v2
	v_or_b32_e32 v2, 51, v0
	v_sub_u32_e32 v2, v2, v232
	v_cmp_gt_u32_e64 s[54:55], 16, v2
	v_or_b32_e32 v2, 24, v0
	v_sub_u32_e32 v2, v2, v232
	v_cmp_gt_u32_e64 s[56:57], 16, v2
	v_or_b32_e32 v2, 56, v0
	v_sub_u32_e32 v2, v2, v232
	v_cmp_gt_u32_e64 s[58:59], 16, v2
	v_or_b32_e32 v2, 25, v0
	v_sub_u32_e32 v2, v2, v232
	v_cmp_gt_u32_e64 s[60:61], 16, v2
	v_or_b32_e32 v2, 57, v0
	v_sub_u32_e32 v2, v2, v232
	v_cmp_gt_u32_e64 s[62:63], 16, v2
	v_or_b32_e32 v2, 26, v0
	v_sub_u32_e32 v2, v2, v232
	v_cmp_gt_u32_e64 s[64:65], 16, v2
	v_or_b32_e32 v2, 58, v0
	v_sub_u32_e32 v2, v2, v232
	v_cmp_gt_u32_e64 s[66:67], 16, v2
	v_or_b32_e32 v2, 27, v0
	v_or_b32_e32 v0, 59, v0
	s_mov_b32 s86, s2
	s_add_i32 s78, s2, -1
	s_min_u32 s2, s0, 4
	v_lshlrev_b32_e32 v197, 4, v230
	v_sub_u32_e32 v0, v0, v232
	s_add_i32 s72, vcc_lo, s2
	v_cmp_gt_u32_e64 s[70:71], 16, v0
	v_sub_u32_e32 v0, v197, v196
	s_mulk_i32 s72, 0x7c
	v_subrev_u32_e32 v0, s72, v0
	s_lshl_b32 s72, s5, 1
	s_and_b32 s72, s72, 0x80
	v_subrev_u32_e32 v0, s72, v0
	v_readlane_b32 s72, v254, 45
	v_sub_u32_e32 v2, v2, v232
	v_mov_b32_e32 v14, v1
	v_add_u32_e32 v198, s72, v0
	s_lshl_b32 s72, s2, 6
	v_mov_b32_e32 v15, v1
	v_cmp_gt_u32_e64 s[68:69], 16, v2
	s_sub_i32 s79, s1, s72
	s_sub_i32 s72, s0, s74
	v_mov_b32_e32 v0, v1
	v_mov_b32_e32 v2, v1
	v_mov_b32_e32 v3, v1
	v_mov_b32_e32 v4, v1
	v_mov_b32_e32 v5, v1
	v_mov_b32_e32 v6, v1
	v_mov_b32_e32 v7, v1
	v_mov_b32_e32 v8, v1
	v_mov_b32_e32 v9, v1
	v_mov_b32_e32 v10, v1
	v_mov_b32_e32 v11, v1
	v_mov_b32_e32 v12, v1
	v_mov_b32_e32 v13, v1
	v_mov_b64_e32 v[62:63], v[14:15]
	v_mov_b64_e32 v[46:47], v[14:15]
	s_mov_b32 s73, 1
	s_mov_b32 s83, -1
	s_mov_b32 s87, s74
	s_sub_i32 s80, s72, s2
	s_mov_b32 s81, 0
	s_movk_i32 s72, 0x4000
	v_mov_b32_e32 v239, 0
	v_mov_b64_e32 v[60:61], v[12:13]
	v_mov_b64_e32 v[58:59], v[10:11]
	v_mov_b64_e32 v[56:57], v[8:9]
	v_mov_b64_e32 v[54:55], v[6:7]
	v_mov_b64_e32 v[52:53], v[4:5]
	v_mov_b64_e32 v[50:51], v[2:3]
	v_mov_b64_e32 v[48:49], v[0:1]
	v_mov_b64_e32 v[44:45], v[12:13]
	v_mov_b64_e32 v[42:43], v[10:11]
	v_mov_b64_e32 v[40:41], v[8:9]
	v_mov_b64_e32 v[38:39], v[6:7]
	v_mov_b64_e32 v[36:37], v[4:5]
	v_mov_b64_e32 v[34:35], v[2:3]
	v_mov_b64_e32 v[32:33], v[0:1]
	s_mov_b32 s74, 0
